# v30 with the attention QK priority raise held through the row-max section (s_setprio 0 moved after the cross-half max)
# speedup vs baseline: 1.0214x; 1.0061x over previous
; #define LAS __attribute__((address_space(3)))
; __device__ __forceinline__ void a2_qk(const LAS unsigned char* kb, const bf16x8 (&qf)[6], const f32x16& cneg, f32x16& st0, f32x16& st1) {
;     { const bf16x8 a0 = *(const LAS bf16x8*)(kb), a1 = *(const LAS bf16x8*)(kb + 32 * AT_KROW);
;       st0 = __builtin_amdgcn_mfma_f32_32x32x16_bf16(a0, qf[0], cneg, 0, 0, 0); st1 = __builtin_amdgcn_mfma_f32_32x32x16_bf16(a1, qf[0], cneg, 0, 0, 0); }
; #pragma unroll
;     for (int s = 1; s < 6; ++s) { const bf16x8 a0 = *(const LAS bf16x8*)(kb + s * 32), a1 = *(const LAS bf16x8*)(kb + 32 * AT_KROW + s * 32);
;         st0 = __builtin_amdgcn_mfma_f32_32x32x16_bf16(a0, qf[s], st0, 0, 0, 0); st1 = __builtin_amdgcn_mfma_f32_32x32x16_bf16(a1, qf[s], st1, 0, 0, 0); }
; }
; __device__ __forceinline__ void attn2_unit(bf16_t* Z, const bf16_t* Hb, const float* rc, const float* rs, LAS unsigned char* lds, int b, int h, int qblk) {
;     ...
;         if (2 * kp + 1 <= cw) {
;             f32x16 sa0, sa1, sb0, sb1; bf16x8 pa[4], pb[4];
;             __builtin_amdgcn_s_setprio(1);
;             a2_qk(kb, qf, cneg, sa0, sa1);
;             a2_qk(kb + 64 * AT_KROW, qf, cneg, sb0, sb1);
;             __builtin_amdgcn_s_setprio(0);
;             const float mt = fmaxf(a2_max(sa0, sa1), a2_max(sb0, sb1));
;             if (kp == 0 || __builtin_amdgcn_ballot_w64(mt > 8.f) != 0ull) {
.LBB0_824:
	s_andn2_b64 vcc, exec, s[6:7]
	s_cbranch_vccnz .LBB0_833
	s_setprio 1
	v_add_u32_e32 v0, v3, v156
	ds_read_b128 v[4:7], v0
	ds_read_b128 v[8:11], v0 offset:6656
	ds_read_b128 v[12:15], v0 offset:32
	ds_read_b128 v[248:251], v0 offset:6688
	v_mov_b64_e32 v[94:95], v[62:63]
	v_mov_b64_e32 v[92:93], v[60:61]
	v_mov_b64_e32 v[90:91], v[58:59]
	v_mov_b64_e32 v[88:89], v[56:57]
	v_mov_b64_e32 v[86:87], v[54:55]
	v_mov_b64_e32 v[84:85], v[52:53]
	v_mov_b64_e32 v[82:83], v[50:51]
	v_mov_b64_e32 v[80:81], v[48:49]
	s_waitcnt lgkmcnt(3)
	v_mfma_f32_32x32x16_bf16 v[112:127], v[4:7], v[128:131], v[48:63]
	ds_read_b128 v[252:255], v0 offset:64
	s_waitcnt lgkmcnt(3)
	v_mfma_f32_32x32x16_bf16 v[96:111], v[8:11], v[128:131], v[48:63]
	ds_read_b128 v[4:7], v0 offset:6720
	s_waitcnt lgkmcnt(3)
	v_mfma_f32_32x32x16_bf16 v[112:127], v[12:15], v[132:135], v[112:127]
	ds_read_b128 v[8:11], v0 offset:96
	s_waitcnt lgkmcnt(3)
	v_mfma_f32_32x32x16_bf16 v[96:111], v[248:251], v[132:135], v[96:111]
	ds_read_b128 v[12:15], v0 offset:6752
	s_waitcnt lgkmcnt(3)
	v_mfma_f32_32x32x16_bf16 v[112:127], v[252:255], v[136:139], v[112:127]
	ds_read_b128 v[248:251], v0 offset:128
	s_waitcnt lgkmcnt(3)
	v_mfma_f32_32x32x16_bf16 v[96:111], v[4:7], v[136:139], v[96:111]
	ds_read_b128 v[252:255], v0 offset:6784
	s_waitcnt lgkmcnt(3)
	v_mfma_f32_32x32x16_bf16 v[112:127], v[8:11], v[140:143], v[112:127]
	ds_read_b128 v[4:7], v0 offset:160
	s_waitcnt lgkmcnt(3)
	v_mfma_f32_32x32x16_bf16 v[96:111], v[12:15], v[140:143], v[96:111]
	ds_read_b128 v[8:11], v0 offset:13312
	s_waitcnt lgkmcnt(3)
	v_mfma_f32_32x32x16_bf16 v[112:127], v[248:251], v[144:147], v[112:127]
	ds_read_b128 v[12:15], v0 offset:6816
	s_waitcnt lgkmcnt(3)
	v_mfma_f32_32x32x16_bf16 v[96:111], v[252:255], v[144:147], v[96:111]
	ds_read_b128 v[248:251], v0 offset:19968
	s_waitcnt lgkmcnt(3)
	v_mfma_f32_32x32x16_bf16 v[112:127], v[4:7], v[148:151], v[112:127]
	ds_read_b128 v[252:255], v0 offset:13344
	s_waitcnt lgkmcnt(3)
	v_mfma_f32_32x32x16_bf16 v[64:79], v[8:11], v[128:131], v[48:63]
	ds_read_b128 v[4:7], v0 offset:20000
	s_waitcnt lgkmcnt(3)
	v_mfma_f32_32x32x16_bf16 v[96:111], v[12:15], v[148:151], v[96:111]
	ds_read_b128 v[8:11], v0 offset:13376
	s_waitcnt lgkmcnt(3)
	v_mfma_f32_32x32x16_bf16 v[80:95], v[248:251], v[128:131], v[80:95]
	ds_read_b128 v[12:15], v0 offset:20032
	s_waitcnt lgkmcnt(3)
	v_mfma_f32_32x32x16_bf16 v[64:79], v[252:255], v[132:135], v[64:79]
	ds_read_b128 v[248:251], v0 offset:13408
	s_waitcnt lgkmcnt(3)
	v_mfma_f32_32x32x16_bf16 v[80:95], v[4:7], v[132:135], v[80:95]
	ds_read_b128 v[252:255], v0 offset:20064
	s_waitcnt lgkmcnt(3)
	v_mfma_f32_32x32x16_bf16 v[64:79], v[8:11], v[136:139], v[64:79]
	ds_read_b128 v[4:7], v0 offset:13440
	s_waitcnt lgkmcnt(3)
	v_mfma_f32_32x32x16_bf16 v[80:95], v[12:15], v[136:139], v[80:95]
	ds_read_b128 v[8:11], v0 offset:20096
	s_waitcnt lgkmcnt(3)
	v_mfma_f32_32x32x16_bf16 v[64:79], v[248:251], v[140:143], v[64:79]
	ds_read_b128 v[12:15], v0 offset:13472
	s_waitcnt lgkmcnt(3)
	v_mfma_f32_32x32x16_bf16 v[80:95], v[252:255], v[140:143], v[80:95]
	ds_read_b128 v[248:251], v0 offset:20128
	s_waitcnt lgkmcnt(3)
	v_mfma_f32_32x32x16_bf16 v[64:79], v[4:7], v[144:147], v[64:79]
	s_waitcnt lgkmcnt(2)
	v_mfma_f32_32x32x16_bf16 v[80:95], v[8:11], v[144:147], v[80:95]
	s_waitcnt lgkmcnt(1)
	v_mfma_f32_32x32x16_bf16 v[64:79], v[12:15], v[148:151], v[64:79]
	s_waitcnt lgkmcnt(0)
	v_mfma_f32_32x32x16_bf16 v[80:95], v[248:251], v[148:151], v[80:95]
	s_nop 0
	v_max_f32_e32 v0, v96, v96
	v_max_f32_e32 v3, v112, v112
	v_max_f32_e32 v0, v3, v0
	s_nop 7
	v_max_f32_e32 v3, v80, v80
	v_max_f32_e32 v4, v64, v64
	v_max_f32_e32 v3, v4, v3
	v_max3_f32 v3, v3, v65, v81
	v_max3_f32 v3, v3, v66, v82
	v_max3_f32 v0, v0, v113, v97
	v_max3_f32 v3, v3, v67, v83
	v_max3_f32 v0, v0, v114, v98
	v_max3_f32 v3, v3, v68, v84
	v_max3_f32 v0, v0, v115, v99
	v_max3_f32 v3, v3, v69, v85
	v_max3_f32 v0, v0, v116, v100
	v_max3_f32 v3, v3, v70, v86
	v_max3_f32 v0, v0, v117, v101
	v_max3_f32 v3, v3, v71, v87
	v_max3_f32 v0, v0, v118, v102
	v_max3_f32 v3, v3, v72, v88
	v_max3_f32 v0, v0, v119, v103
	v_max3_f32 v3, v3, v73, v89
	v_max3_f32 v0, v0, v120, v104
	v_max3_f32 v3, v3, v74, v90
	v_max3_f32 v0, v0, v121, v105
	v_max3_f32 v3, v3, v75, v91
	v_max3_f32 v0, v0, v122, v106
	v_max3_f32 v3, v3, v76, v92
	v_max3_f32 v0, v0, v123, v107
	v_max3_f32 v3, v3, v77, v93
	v_max3_f32 v0, v0, v124, v108
	v_max3_f32 v3, v3, v78, v94
	v_max3_f32 v3, v3, v79, v95
	v_max3_f32 v0, v0, v125, v109
	v_max3_f32 v0, v0, v126, v110
	v_max3_f32 v0, v0, v127, v111
	s_cmp_eq_u32 s65, 1
	v_max_f32_e32 v3, v3, v0
	v_mov_b32_e32 v4, v3
	v_mov_b32_e32 v5, v3
	s_cselect_b64 s[34:35], -1, 0
	s_cmp_lg_u32 s65, 1
	v_permlane32_swap_b32_e32 v4, v5
	s_setprio 0
	v_max_f32_e32 v3, v4, v5
	s_cbranch_scc0 .LBB0_835
	v_cmp_lt_f32_e32 vcc, s53, v3
	s_mov_b64 s[24:25], 0
	s_mov_b64 s[6:7], 0
	s_cbranch_vccz .LBB0_828
	v_max_f32_e32 v0, v3, v3
	v_max_f32_e32 v0, 0, v0
	s_mov_b64 s[6:7], -1

; #define LAS __attribute__((address_space(3)))
; __device__ __forceinline__ void a2_qk(const LAS unsigned char* kb, const bf16x8 (&qf)[6], const f32x16& cneg, f32x16& st0, f32x16& st1) {
;     { const bf16x8 a0 = *(const LAS bf16x8*)(kb), a1 = *(const LAS bf16x8*)(kb + 32 * AT_KROW);
;       st0 = __builtin_amdgcn_mfma_f32_32x32x16_bf16(a0, qf[0], cneg, 0, 0, 0); st1 = __builtin_amdgcn_mfma_f32_32x32x16_bf16(a1, qf[0], cneg, 0, 0, 0); }
; #pragma unroll
;     for (int s = 1; s < 6; ++s) { const bf16x8 a0 = *(const LAS bf16x8*)(kb + s * 32), a1 = *(const LAS bf16x8*)(kb + 32 * AT_KROW + s * 32);
;         st0 = __builtin_amdgcn_mfma_f32_32x32x16_bf16(a0, qf[s], st0, 0, 0, 0); st1 = __builtin_amdgcn_mfma_f32_32x32x16_bf16(a1, qf[s], st1, 0, 0, 0); }
; }
; __device__ __forceinline__ void attn2_unit(bf16_t* Z, const bf16_t* Hb, const float* rc, const float* rs, LAS unsigned char* lds, int b, int h, int qblk) {
;     ...
;         if (2 * kp + 1 <= cw) {
;             f32x16 sa0, sa1, sb0, sb1; bf16x8 pa[4], pb[4];
;             __builtin_amdgcn_s_setprio(1);
;             a2_qk(kb, qf, cneg, sa0, sa1);
;             a2_qk(kb + 64 * AT_KROW, qf, cneg, sb0, sb1);
;             __builtin_amdgcn_s_setprio(0);
;             const float mt = fmaxf(a2_max(sa0, sa1), a2_max(sb0, sb1));
;             if (kp == 0 || __builtin_amdgcn_ballot_w64(mt > 8.f) != 0ull) {
.LBB0_870:
	s_andn2_b64 vcc, exec, s[6:7]
	s_cbranch_vccnz .LBB0_879
	s_setprio 1
	v_add_u32_e32 v0, v3, v156
	ds_read_b128 v[4:7], v0
	ds_read_b128 v[8:11], v0 offset:6656
	ds_read_b128 v[12:15], v0 offset:32
	ds_read_b128 v[248:251], v0 offset:6688
	v_mov_b64_e32 v[94:95], v[62:63]
	v_mov_b64_e32 v[92:93], v[60:61]
	v_mov_b64_e32 v[90:91], v[58:59]
	v_mov_b64_e32 v[88:89], v[56:57]
	v_mov_b64_e32 v[86:87], v[54:55]
	v_mov_b64_e32 v[84:85], v[52:53]
	v_mov_b64_e32 v[82:83], v[50:51]
	v_mov_b64_e32 v[80:81], v[48:49]
	s_waitcnt lgkmcnt(3)
	v_mfma_f32_32x32x16_bf16 v[112:127], v[4:7], v[128:131], v[48:63]
	ds_read_b128 v[252:255], v0 offset:64
	s_waitcnt lgkmcnt(3)
	v_mfma_f32_32x32x16_bf16 v[96:111], v[8:11], v[128:131], v[48:63]
	ds_read_b128 v[4:7], v0 offset:6720
	s_waitcnt lgkmcnt(3)
	v_mfma_f32_32x32x16_bf16 v[112:127], v[12:15], v[132:135], v[112:127]
	ds_read_b128 v[8:11], v0 offset:96
	s_waitcnt lgkmcnt(3)
	v_mfma_f32_32x32x16_bf16 v[96:111], v[248:251], v[132:135], v[96:111]
	ds_read_b128 v[12:15], v0 offset:6752
	s_waitcnt lgkmcnt(3)
	v_mfma_f32_32x32x16_bf16 v[112:127], v[252:255], v[136:139], v[112:127]
	ds_read_b128 v[248:251], v0 offset:128
	s_waitcnt lgkmcnt(3)
	v_mfma_f32_32x32x16_bf16 v[96:111], v[4:7], v[136:139], v[96:111]
	ds_read_b128 v[252:255], v0 offset:6784
	s_waitcnt lgkmcnt(3)
	v_mfma_f32_32x32x16_bf16 v[112:127], v[8:11], v[140:143], v[112:127]
	ds_read_b128 v[4:7], v0 offset:160
	s_waitcnt lgkmcnt(3)
	v_mfma_f32_32x32x16_bf16 v[96:111], v[12:15], v[140:143], v[96:111]
	ds_read_b128 v[8:11], v0 offset:13312
	s_waitcnt lgkmcnt(3)
	v_mfma_f32_32x32x16_bf16 v[112:127], v[248:251], v[144:147], v[112:127]
	ds_read_b128 v[12:15], v0 offset:6816
	s_waitcnt lgkmcnt(3)
	v_mfma_f32_32x32x16_bf16 v[96:111], v[252:255], v[144:147], v[96:111]
	ds_read_b128 v[248:251], v0 offset:19968
	s_waitcnt lgkmcnt(3)
	v_mfma_f32_32x32x16_bf16 v[112:127], v[4:7], v[148:151], v[112:127]
	ds_read_b128 v[252:255], v0 offset:13344
	s_waitcnt lgkmcnt(3)
	v_mfma_f32_32x32x16_bf16 v[64:79], v[8:11], v[128:131], v[48:63]
	ds_read_b128 v[4:7], v0 offset:20000
	s_waitcnt lgkmcnt(3)
	v_mfma_f32_32x32x16_bf16 v[96:111], v[12:15], v[148:151], v[96:111]
	ds_read_b128 v[8:11], v0 offset:13376
	s_waitcnt lgkmcnt(3)
	v_mfma_f32_32x32x16_bf16 v[80:95], v[248:251], v[128:131], v[80:95]
	ds_read_b128 v[12:15], v0 offset:20032
	s_waitcnt lgkmcnt(3)
	v_mfma_f32_32x32x16_bf16 v[64:79], v[252:255], v[132:135], v[64:79]
	ds_read_b128 v[248:251], v0 offset:13408
	s_waitcnt lgkmcnt(3)
	v_mfma_f32_32x32x16_bf16 v[80:95], v[4:7], v[132:135], v[80:95]
	ds_read_b128 v[252:255], v0 offset:20064
	s_waitcnt lgkmcnt(3)
	v_mfma_f32_32x32x16_bf16 v[64:79], v[8:11], v[136:139], v[64:79]
	ds_read_b128 v[4:7], v0 offset:13440
	s_waitcnt lgkmcnt(3)
	v_mfma_f32_32x32x16_bf16 v[80:95], v[12:15], v[136:139], v[80:95]
	ds_read_b128 v[8:11], v0 offset:20096
	s_waitcnt lgkmcnt(3)
	v_mfma_f32_32x32x16_bf16 v[64:79], v[248:251], v[140:143], v[64:79]
	ds_read_b128 v[12:15], v0 offset:13472
	s_waitcnt lgkmcnt(3)
	v_mfma_f32_32x32x16_bf16 v[80:95], v[252:255], v[140:143], v[80:95]
	ds_read_b128 v[248:251], v0 offset:20128
	s_waitcnt lgkmcnt(3)
	v_mfma_f32_32x32x16_bf16 v[64:79], v[4:7], v[144:147], v[64:79]
	s_waitcnt lgkmcnt(2)
	v_mfma_f32_32x32x16_bf16 v[80:95], v[8:11], v[144:147], v[80:95]
	s_waitcnt lgkmcnt(1)
	v_mfma_f32_32x32x16_bf16 v[64:79], v[12:15], v[148:151], v[64:79]
	s_waitcnt lgkmcnt(0)
	v_mfma_f32_32x32x16_bf16 v[80:95], v[248:251], v[148:151], v[80:95]
	s_nop 0
	v_max_f32_e32 v0, v96, v96
	v_max_f32_e32 v3, v112, v112
	v_max_f32_e32 v0, v3, v0
	s_nop 7
	v_max_f32_e32 v3, v80, v80
	v_max_f32_e32 v4, v64, v64
	v_max_f32_e32 v3, v4, v3
	v_max3_f32 v3, v3, v65, v81
	v_max3_f32 v3, v3, v66, v82
	v_max3_f32 v0, v0, v113, v97
	v_max3_f32 v3, v3, v67, v83
	v_max3_f32 v0, v0, v114, v98
	v_max3_f32 v3, v3, v68, v84
	v_max3_f32 v0, v0, v115, v99
	v_max3_f32 v3, v3, v69, v85
	v_max3_f32 v0, v0, v116, v100
	v_max3_f32 v3, v3, v70, v86
	v_max3_f32 v0, v0, v117, v101
	v_max3_f32 v3, v3, v71, v87
	v_max3_f32 v0, v0, v118, v102
	v_max3_f32 v3, v3, v72, v88
	v_max3_f32 v0, v0, v119, v103
	v_max3_f32 v3, v3, v73, v89
	v_max3_f32 v0, v0, v120, v104
	v_max3_f32 v3, v3, v74, v90
	v_max3_f32 v0, v0, v121, v105
	v_max3_f32 v3, v3, v75, v91
	v_max3_f32 v0, v0, v122, v106
	v_max3_f32 v3, v3, v76, v92
	v_max3_f32 v0, v0, v123, v107
	v_max3_f32 v3, v3, v77, v93
	v_max3_f32 v0, v0, v124, v108
	v_max3_f32 v3, v3, v78, v94
	v_max3_f32 v3, v3, v79, v95
	v_max3_f32 v0, v0, v125, v109
	v_max3_f32 v0, v0, v126, v110
	v_max3_f32 v0, v0, v127, v111
	s_cmp_eq_u32 s35, 1
	v_max_f32_e32 v3, v3, v0
	v_mov_b32_e32 v4, v3
	v_mov_b32_e32 v5, v3
	s_cselect_b64 s[28:29], -1, 0
	s_cmp_lg_u32 s35, 1
	v_permlane32_swap_b32_e32 v4, v5
	s_setprio 0
	v_max_f32_e32 v3, v4, v5
	s_cbranch_scc0 .LBB0_881
	v_cmp_lt_f32_e32 vcc, s53, v3
	s_mov_b64 s[24:25], 0
	s_mov_b64 s[6:7], 0
	s_cbranch_vccz .LBB0_874
	v_max_f32_e32 v0, v3, v3
	v_max_f32_e32 v0, 0, v0
	s_mov_b64 s[6:7], -1

; #define LAS __attribute__((address_space(3)))
; __device__ __forceinline__ void a2_qk(const LAS unsigned char* kb, const bf16x8 (&qf)[6], const f32x16& cneg, f32x16& st0, f32x16& st1) {
;     { const bf16x8 a0 = *(const LAS bf16x8*)(kb), a1 = *(const LAS bf16x8*)(kb + 32 * AT_KROW);
;       st0 = __builtin_amdgcn_mfma_f32_32x32x16_bf16(a0, qf[0], cneg, 0, 0, 0); st1 = __builtin_amdgcn_mfma_f32_32x32x16_bf16(a1, qf[0], cneg, 0, 0, 0); }
; #pragma unroll
;     for (int s = 1; s < 6; ++s) { const bf16x8 a0 = *(const LAS bf16x8*)(kb + s * 32), a1 = *(const LAS bf16x8*)(kb + 32 * AT_KROW + s * 32);
;         st0 = __builtin_amdgcn_mfma_f32_32x32x16_bf16(a0, qf[s], st0, 0, 0, 0); st1 = __builtin_amdgcn_mfma_f32_32x32x16_bf16(a1, qf[s], st1, 0, 0, 0); }
; }
; __device__ __forceinline__ void attn2_unit(bf16_t* Z, const bf16_t* Hb, const float* rc, const float* rs, LAS unsigned char* lds, int b, int h, int qblk) {
;     ...
;         if (2 * kp + 1 <= cw) {
;             f32x16 sa0, sa1, sb0, sb1; bf16x8 pa[4], pb[4];
;             __builtin_amdgcn_s_setprio(1);
;             a2_qk(kb, qf, cneg, sa0, sa1);
;             a2_qk(kb + 64 * AT_KROW, qf, cneg, sb0, sb1);
;             __builtin_amdgcn_s_setprio(0);
;             const float mt = fmaxf(a2_max(sa0, sa1), a2_max(sb0, sb1));
;             if (kp == 0 || __builtin_amdgcn_ballot_w64(mt > 8.f) != 0ull) {
.LBB0_2235:
	s_andn2_b64 vcc, exec, s[6:7]
	s_cbranch_vccnz .LBB0_2244
	s_setprio 1
	v_add_u32_e32 v0, v3, v156
	ds_read_b128 v[4:7], v0
	ds_read_b128 v[8:11], v0 offset:6656
	ds_read_b128 v[12:15], v0 offset:32
	ds_read_b128 v[248:251], v0 offset:6688
	v_mov_b64_e32 v[94:95], v[62:63]
	v_mov_b64_e32 v[92:93], v[60:61]
	v_mov_b64_e32 v[90:91], v[58:59]
	v_mov_b64_e32 v[88:89], v[56:57]
	v_mov_b64_e32 v[86:87], v[54:55]
	v_mov_b64_e32 v[84:85], v[52:53]
	v_mov_b64_e32 v[82:83], v[50:51]
	v_mov_b64_e32 v[80:81], v[48:49]
	s_waitcnt lgkmcnt(3)
	v_mfma_f32_32x32x16_bf16 v[112:127], v[4:7], v[128:131], v[48:63]
	ds_read_b128 v[252:255], v0 offset:64
	s_waitcnt lgkmcnt(3)
	v_mfma_f32_32x32x16_bf16 v[96:111], v[8:11], v[128:131], v[48:63]
	ds_read_b128 v[4:7], v0 offset:6720
	s_waitcnt lgkmcnt(3)
	v_mfma_f32_32x32x16_bf16 v[112:127], v[12:15], v[132:135], v[112:127]
	ds_read_b128 v[8:11], v0 offset:96
	s_waitcnt lgkmcnt(3)
	v_mfma_f32_32x32x16_bf16 v[96:111], v[248:251], v[132:135], v[96:111]
	ds_read_b128 v[12:15], v0 offset:6752
	s_waitcnt lgkmcnt(3)
	v_mfma_f32_32x32x16_bf16 v[112:127], v[252:255], v[136:139], v[112:127]
	ds_read_b128 v[248:251], v0 offset:128
	s_waitcnt lgkmcnt(3)
	v_mfma_f32_32x32x16_bf16 v[96:111], v[4:7], v[136:139], v[96:111]
	ds_read_b128 v[252:255], v0 offset:6784
	s_waitcnt lgkmcnt(3)
	v_mfma_f32_32x32x16_bf16 v[112:127], v[8:11], v[140:143], v[112:127]
	ds_read_b128 v[4:7], v0 offset:160
	s_waitcnt lgkmcnt(3)
	v_mfma_f32_32x32x16_bf16 v[96:111], v[12:15], v[140:143], v[96:111]
	ds_read_b128 v[8:11], v0 offset:13312
	s_waitcnt lgkmcnt(3)
	v_mfma_f32_32x32x16_bf16 v[112:127], v[248:251], v[144:147], v[112:127]
	ds_read_b128 v[12:15], v0 offset:6816
	s_waitcnt lgkmcnt(3)
	v_mfma_f32_32x32x16_bf16 v[96:111], v[252:255], v[144:147], v[96:111]
	ds_read_b128 v[248:251], v0 offset:19968
	s_waitcnt lgkmcnt(3)
	v_mfma_f32_32x32x16_bf16 v[112:127], v[4:7], v[148:151], v[112:127]
	ds_read_b128 v[252:255], v0 offset:13344
	s_waitcnt lgkmcnt(3)
	v_mfma_f32_32x32x16_bf16 v[64:79], v[8:11], v[128:131], v[48:63]
	ds_read_b128 v[4:7], v0 offset:20000
	s_waitcnt lgkmcnt(3)
	v_mfma_f32_32x32x16_bf16 v[96:111], v[12:15], v[148:151], v[96:111]
	ds_read_b128 v[8:11], v0 offset:13376
	s_waitcnt lgkmcnt(3)
	v_mfma_f32_32x32x16_bf16 v[80:95], v[248:251], v[128:131], v[80:95]
	ds_read_b128 v[12:15], v0 offset:20032
	s_waitcnt lgkmcnt(3)
	v_mfma_f32_32x32x16_bf16 v[64:79], v[252:255], v[132:135], v[64:79]
	ds_read_b128 v[248:251], v0 offset:13408
	s_waitcnt lgkmcnt(3)
	v_mfma_f32_32x32x16_bf16 v[80:95], v[4:7], v[132:135], v[80:95]
	ds_read_b128 v[252:255], v0 offset:20064
	s_waitcnt lgkmcnt(3)
	v_mfma_f32_32x32x16_bf16 v[64:79], v[8:11], v[136:139], v[64:79]
	ds_read_b128 v[4:7], v0 offset:13440
	s_waitcnt lgkmcnt(3)
	v_mfma_f32_32x32x16_bf16 v[80:95], v[12:15], v[136:139], v[80:95]
	ds_read_b128 v[8:11], v0 offset:20096
	s_waitcnt lgkmcnt(3)
	v_mfma_f32_32x32x16_bf16 v[64:79], v[248:251], v[140:143], v[64:79]
	ds_read_b128 v[12:15], v0 offset:13472
	s_waitcnt lgkmcnt(3)
	v_mfma_f32_32x32x16_bf16 v[80:95], v[252:255], v[140:143], v[80:95]
	ds_read_b128 v[248:251], v0 offset:20128
	s_waitcnt lgkmcnt(3)
	v_mfma_f32_32x32x16_bf16 v[64:79], v[4:7], v[144:147], v[64:79]
	s_waitcnt lgkmcnt(2)
	v_mfma_f32_32x32x16_bf16 v[80:95], v[8:11], v[144:147], v[80:95]
	s_waitcnt lgkmcnt(1)
	v_mfma_f32_32x32x16_bf16 v[64:79], v[12:15], v[148:151], v[64:79]
	s_waitcnt lgkmcnt(0)
	v_mfma_f32_32x32x16_bf16 v[80:95], v[248:251], v[148:151], v[80:95]
	s_nop 0
	v_max_f32_e32 v0, v96, v96
	v_max_f32_e32 v3, v112, v112
	v_max_f32_e32 v0, v3, v0
	s_nop 7
	v_max_f32_e32 v3, v80, v80
	v_max_f32_e32 v4, v64, v64
	v_max_f32_e32 v3, v4, v3
	v_max3_f32 v3, v3, v65, v81
	v_max3_f32 v3, v3, v66, v82
	v_max3_f32 v0, v0, v113, v97
	v_max3_f32 v3, v3, v67, v83
	v_max3_f32 v0, v0, v114, v98
	v_max3_f32 v3, v3, v68, v84
	v_max3_f32 v0, v0, v115, v99
	v_max3_f32 v3, v3, v69, v85
	v_max3_f32 v0, v0, v116, v100
	v_max3_f32 v3, v3, v70, v86
	v_max3_f32 v0, v0, v117, v101
	v_max3_f32 v3, v3, v71, v87
	v_max3_f32 v0, v0, v118, v102
	v_max3_f32 v3, v3, v72, v88
	v_max3_f32 v0, v0, v119, v103
	v_max3_f32 v3, v3, v73, v89
	v_max3_f32 v0, v0, v120, v104
	v_max3_f32 v3, v3, v74, v90
	v_max3_f32 v0, v0, v121, v105
	v_max3_f32 v3, v3, v75, v91
	v_max3_f32 v0, v0, v122, v106
	v_max3_f32 v3, v3, v76, v92
	v_max3_f32 v0, v0, v123, v107
	v_max3_f32 v3, v3, v77, v93
	v_max3_f32 v0, v0, v124, v108
	v_max3_f32 v3, v3, v78, v94
	v_max3_f32 v3, v3, v79, v95
	v_max3_f32 v0, v0, v125, v109
	v_max3_f32 v0, v0, v126, v110
	v_max3_f32 v0, v0, v127, v111
	s_cmp_eq_u32 s47, 1
	v_max_f32_e32 v3, v3, v0
	v_mov_b32_e32 v4, v3
	v_mov_b32_e32 v5, v3
	s_cselect_b64 s[30:31], -1, 0
	s_cmp_lg_u32 s47, 1
	v_permlane32_swap_b32_e32 v4, v5
	s_setprio 0
	v_max_f32_e32 v3, v4, v5
	s_cbranch_scc0 .LBB0_2246
	v_cmp_lt_f32_e32 vcc, s41, v3
	s_mov_b64 s[24:25], 0
	s_mov_b64 s[6:7], 0
	s_cbranch_vccz .LBB0_2239
	v_max_f32_e32 v0, v3, v3
	v_max_f32_e32 v0, 0, v0
	s_mov_b64 s[6:7], -1

; #define LAS __attribute__((address_space(3)))
; __device__ __forceinline__ void a2_qk(const LAS unsigned char* kb, const bf16x8 (&qf)[6], const f32x16& cneg, f32x16& st0, f32x16& st1) {
;     { const bf16x8 a0 = *(const LAS bf16x8*)(kb), a1 = *(const LAS bf16x8*)(kb + 32 * AT_KROW);
;       st0 = __builtin_amdgcn_mfma_f32_32x32x16_bf16(a0, qf[0], cneg, 0, 0, 0); st1 = __builtin_amdgcn_mfma_f32_32x32x16_bf16(a1, qf[0], cneg, 0, 0, 0); }
; #pragma unroll
;     for (int s = 1; s < 6; ++s) { const bf16x8 a0 = *(const LAS bf16x8*)(kb + s * 32), a1 = *(const LAS bf16x8*)(kb + 32 * AT_KROW + s * 32);
;         st0 = __builtin_amdgcn_mfma_f32_32x32x16_bf16(a0, qf[s], st0, 0, 0, 0); st1 = __builtin_amdgcn_mfma_f32_32x32x16_bf16(a1, qf[s], st1, 0, 0, 0); }
; }
; __device__ __forceinline__ void attn2_unit(bf16_t* Z, const bf16_t* Hb, const float* rc, const float* rs, LAS unsigned char* lds, int b, int h, int qblk) {
;     ...
;         if (2 * kp + 1 <= cw) {
;             f32x16 sa0, sa1, sb0, sb1; bf16x8 pa[4], pb[4];
;             __builtin_amdgcn_s_setprio(1);
;             a2_qk(kb, qf, cneg, sa0, sa1);
;             a2_qk(kb + 64 * AT_KROW, qf, cneg, sb0, sb1);
;             __builtin_amdgcn_s_setprio(0);
;             const float mt = fmaxf(a2_max(sa0, sa1), a2_max(sb0, sb1));
;             if (kp == 0 || __builtin_amdgcn_ballot_w64(mt > 8.f) != 0ull) {
.LBB0_2281:
	s_andn2_b64 vcc, exec, s[6:7]
	s_cbranch_vccnz .LBB0_2290
	s_setprio 1
	v_add_u32_e32 v0, v3, v156
	ds_read_b128 v[4:7], v0
	ds_read_b128 v[8:11], v0 offset:6656
	ds_read_b128 v[12:15], v0 offset:32
	ds_read_b128 v[248:251], v0 offset:6688
	v_mov_b64_e32 v[94:95], v[62:63]
	v_mov_b64_e32 v[92:93], v[60:61]
	v_mov_b64_e32 v[90:91], v[58:59]
	v_mov_b64_e32 v[88:89], v[56:57]
	v_mov_b64_e32 v[86:87], v[54:55]
	v_mov_b64_e32 v[84:85], v[52:53]
	v_mov_b64_e32 v[82:83], v[50:51]
	v_mov_b64_e32 v[80:81], v[48:49]
	s_waitcnt lgkmcnt(3)
	v_mfma_f32_32x32x16_bf16 v[112:127], v[4:7], v[128:131], v[48:63]
	ds_read_b128 v[252:255], v0 offset:64
	s_waitcnt lgkmcnt(3)
	v_mfma_f32_32x32x16_bf16 v[96:111], v[8:11], v[128:131], v[48:63]
	ds_read_b128 v[4:7], v0 offset:6720
	s_waitcnt lgkmcnt(3)
	v_mfma_f32_32x32x16_bf16 v[112:127], v[12:15], v[132:135], v[112:127]
	ds_read_b128 v[8:11], v0 offset:96
	s_waitcnt lgkmcnt(3)
	v_mfma_f32_32x32x16_bf16 v[96:111], v[248:251], v[132:135], v[96:111]
	ds_read_b128 v[12:15], v0 offset:6752
	s_waitcnt lgkmcnt(3)
	v_mfma_f32_32x32x16_bf16 v[112:127], v[252:255], v[136:139], v[112:127]
	ds_read_b128 v[248:251], v0 offset:128
	s_waitcnt lgkmcnt(3)
	v_mfma_f32_32x32x16_bf16 v[96:111], v[4:7], v[136:139], v[96:111]
	ds_read_b128 v[252:255], v0 offset:6784
	s_waitcnt lgkmcnt(3)
	v_mfma_f32_32x32x16_bf16 v[112:127], v[8:11], v[140:143], v[112:127]
	ds_read_b128 v[4:7], v0 offset:160
	s_waitcnt lgkmcnt(3)
	v_mfma_f32_32x32x16_bf16 v[96:111], v[12:15], v[140:143], v[96:111]
	ds_read_b128 v[8:11], v0 offset:13312
	s_waitcnt lgkmcnt(3)
	v_mfma_f32_32x32x16_bf16 v[112:127], v[248:251], v[144:147], v[112:127]
	ds_read_b128 v[12:15], v0 offset:6816
	s_waitcnt lgkmcnt(3)
	v_mfma_f32_32x32x16_bf16 v[96:111], v[252:255], v[144:147], v[96:111]
	ds_read_b128 v[248:251], v0 offset:19968
	s_waitcnt lgkmcnt(3)
	v_mfma_f32_32x32x16_bf16 v[112:127], v[4:7], v[148:151], v[112:127]
	ds_read_b128 v[252:255], v0 offset:13344
	s_waitcnt lgkmcnt(3)
	v_mfma_f32_32x32x16_bf16 v[64:79], v[8:11], v[128:131], v[48:63]
	ds_read_b128 v[4:7], v0 offset:20000
	s_waitcnt lgkmcnt(3)
	v_mfma_f32_32x32x16_bf16 v[96:111], v[12:15], v[148:151], v[96:111]
	ds_read_b128 v[8:11], v0 offset:13376
	s_waitcnt lgkmcnt(3)
	v_mfma_f32_32x32x16_bf16 v[80:95], v[248:251], v[128:131], v[80:95]
	ds_read_b128 v[12:15], v0 offset:20032
	s_waitcnt lgkmcnt(3)
	v_mfma_f32_32x32x16_bf16 v[64:79], v[252:255], v[132:135], v[64:79]
	ds_read_b128 v[248:251], v0 offset:13408
	s_waitcnt lgkmcnt(3)
	v_mfma_f32_32x32x16_bf16 v[80:95], v[4:7], v[132:135], v[80:95]
	ds_read_b128 v[252:255], v0 offset:20064
	s_waitcnt lgkmcnt(3)
	v_mfma_f32_32x32x16_bf16 v[64:79], v[8:11], v[136:139], v[64:79]
	ds_read_b128 v[4:7], v0 offset:13440
	s_waitcnt lgkmcnt(3)
	v_mfma_f32_32x32x16_bf16 v[80:95], v[12:15], v[136:139], v[80:95]
	ds_read_b128 v[8:11], v0 offset:20096
	s_waitcnt lgkmcnt(3)
	v_mfma_f32_32x32x16_bf16 v[64:79], v[248:251], v[140:143], v[64:79]
	ds_read_b128 v[12:15], v0 offset:13472
	s_waitcnt lgkmcnt(3)
	v_mfma_f32_32x32x16_bf16 v[80:95], v[252:255], v[140:143], v[80:95]
	ds_read_b128 v[248:251], v0 offset:20128
	s_waitcnt lgkmcnt(3)
	v_mfma_f32_32x32x16_bf16 v[64:79], v[4:7], v[144:147], v[64:79]
	s_waitcnt lgkmcnt(2)
	v_mfma_f32_32x32x16_bf16 v[80:95], v[8:11], v[144:147], v[80:95]
	s_waitcnt lgkmcnt(1)
	v_mfma_f32_32x32x16_bf16 v[64:79], v[12:15], v[148:151], v[64:79]
	s_waitcnt lgkmcnt(0)
	v_mfma_f32_32x32x16_bf16 v[80:95], v[248:251], v[148:151], v[80:95]
	s_nop 0
	v_max_f32_e32 v0, v96, v96
	v_max_f32_e32 v3, v112, v112
	v_max_f32_e32 v0, v3, v0
	s_nop 7
	v_max_f32_e32 v3, v80, v80
	v_max_f32_e32 v4, v64, v64
	v_max_f32_e32 v3, v4, v3
	v_max3_f32 v3, v3, v65, v81
	v_max3_f32 v3, v3, v66, v82
	v_max3_f32 v0, v0, v113, v97
	v_max3_f32 v3, v3, v67, v83
	v_max3_f32 v0, v0, v114, v98
	v_max3_f32 v3, v3, v68, v84
	v_max3_f32 v0, v0, v115, v99
	v_max3_f32 v3, v3, v69, v85
	v_max3_f32 v0, v0, v116, v100
	v_max3_f32 v3, v3, v70, v86
	v_max3_f32 v0, v0, v117, v101
	v_max3_f32 v3, v3, v71, v87
	v_max3_f32 v0, v0, v118, v102
	v_max3_f32 v3, v3, v72, v88
	v_max3_f32 v0, v0, v119, v103
	v_max3_f32 v3, v3, v73, v89
	v_max3_f32 v0, v0, v120, v104
	v_max3_f32 v3, v3, v74, v90
	v_max3_f32 v0, v0, v121, v105
	v_max3_f32 v3, v3, v75, v91
	v_max3_f32 v0, v0, v122, v106
	v_max3_f32 v3, v3, v76, v92
	v_max3_f32 v0, v0, v123, v107
	v_max3_f32 v3, v3, v77, v93
	v_max3_f32 v0, v0, v124, v108
	v_max3_f32 v3, v3, v78, v94
	v_max3_f32 v3, v3, v79, v95
	v_max3_f32 v0, v0, v125, v109
	v_max3_f32 v0, v0, v126, v110
	v_max3_f32 v0, v0, v127, v111
	s_cmp_eq_u32 s31, 1
	v_max_f32_e32 v3, v3, v0
	v_mov_b32_e32 v4, v3
	v_mov_b32_e32 v5, v3
	s_cselect_b64 s[26:27], -1, 0
	s_cmp_lg_u32 s31, 1
	v_permlane32_swap_b32_e32 v4, v5
	s_setprio 0
	v_max_f32_e32 v3, v4, v5
	s_cbranch_scc0 .LBB0_2292
	v_cmp_lt_f32_e32 vcc, s41, v3
	s_mov_b64 s[24:25], 0
	s_mov_b64 s[6:7], 0
	s_cbranch_vccz .LBB0_2285
	v_max_f32_e32 v0, v3, v3
	v_max_f32_e32 v0, 0, v0
	s_mov_b64 s[6:7], -1
